# P4 epilogue fully hand-written (plain, product, rope, sigmoid tiles), rotated row-group order, full-line stores through the idle As[1][1] stage slot
# speedup vs baseline: 1.0066x; 1.0025x over previous
; #define PG8_LAS __attribute__((address_space(3)))
;     __device__ __forceinline__ void operator()(const f32x4 (&acc)[2][2][4][2], const Unit& u, int wr, int wc, int fr, int fq) const {
;     ...
;         const PG8_LAS float* bp = (const PG8_LAS float*)(scr + 16384) + tcol;
;         const f32x4 ba0 = *(const PG8_LAS f32x4*)bp, ba1 = *(const PG8_LAS f32x4*)(bp + 4), bb0 = *(const PG8_LAS f32x4*)(bp + HALF), bb1 = *(const PG8_LAS f32x4*)(bp + HALF + 4);
;         int mode, pitch, c0, c1; bf16_t* dst;
;         if (pn < 4)       { mode = 0; dst = BG;  pitch = DM;  c0 = pn * BM + wc * 64 + fq * 8; c1 = c0 + 32; }
;         else if (pn < 12) { mode = 1; dst = CU;  pitch = DM;  c0 = (pn - 4) * HALF + tcol; c1 = c0; }
;         else if (pn < 16) { mode = 2; dst = Q;   pitch = DM;  c0 = (4 * (pn - 12) + wc) * 64 + fq * 8; c1 = c0 + 32; }
;         else if (pn < 17) { mode = 2; dst = K;   pitch = 256; c0 = wc * 64 + fq * 8; c1 = c0 + 32; }
;         else if (pn < 18) { mode = 0; dst = V;   pitch = 256; c0 = wc * 64 + fq * 8; c1 = c0 + 32; }
;         else              { mode = 3; dst = SZC; pitch = DM;  c0 = (pn - 18) * HALF + tcol; c1 = c0; }
.LBB0_444:
	v_mov_b32_e32 v175, v1
	v_mov_b32_e32 v147, v201
	s_cmp_gt_i32 s6, 3
	v_lshlrev_b32_e32 v164, 3, v147
	v_add_u32_e32 v146, s80, v164
	v_lshl_add_u32 v42, v146, 2, 0
	v_add_u32_e32 v42, 0x24000, v42
	ds_read_b128 v[54:57], v42
	ds_read_b128 v[50:53], v42 offset:16
	ds_read_b128 v[46:49], v42 offset:512
	ds_read_b128 v[42:45], v42 offset:528
	s_cmp_gt_u32 s6, 17
	s_cbranch_scc1 .Lp4e_m3
	s_add_i32 s5, s6, -4
	s_cmp_lt_u32 s5, 8
	s_cbranch_scc1 .Lp4e_m1
	s_add_i32 s5, s6, -12
	s_cmp_lt_u32 s5, 5
	s_cbranch_scc1 .Lp4e_m2
	s_branch .Lp4e_m0
	s_mov_b64 s[60:61], -1
	s_cbranch_scc0 .LBB0_460
	s_cmp_gt_u32 s6, 11
	s_mov_b64 s[56:57], -1
	s_cbranch_scc0 .LBB0_458
	s_cmp_gt_u32 s6, 15
	s_cbranch_scc0 .LBB0_455
	s_cmp_lg_u32 s6, 16
	s_mov_b64 s[54:55], -1
	s_cbranch_scc0 .LBB0_453
	s_mov_b64 s[58:59], -1
	s_cmp_gt_u32 s6, 17
	s_mov_b64 s[10:11], -1
	s_cbranch_scc0 .LBB0_450
	s_lshl_b32 s5, s6, 7
	s_addk_i32 s5, 0xf700
	v_add_u32_e32 v204, s5, v146
	s_mov_b64 s[10:11], 0

; __device__ __forceinline__ void store_lines(PG8_LAS unsigned char* stg, const u32x4 P0, const u32x4 P1, int fr, int fq, bf16_t* seg0, int pitch) {
;     const int ln = fq * 16 + fr;
; #pragma unroll
;     for (int h = 0; h < 2; ++h) {
;         if ((fr >> 3) == h) { *(PG8_LAS u32x4*)(stg + (fr & 7) * 128 + fq * 16) = P0; *(PG8_LAS u32x4*)(stg + (fr & 7) * 128 + 64 + fq * 16) = P1; }
;         __builtin_amdgcn_wave_barrier(); asm volatile("" ::: "memory");
;         const u32x4 v = *(const PG8_LAS u32x4*)(stg + ln * 16);
;         __builtin_amdgcn_wave_barrier(); asm volatile("" ::: "memory");
;     __device__ __forceinline__ void operator()(const f32x4 (&acc)[2][2][4][2], const Unit& u, int wr, int wc, int fr, int fq) const {
;     ...
;         EPI_ROWS { rsv[ai][m] = rstd_lds(scr, EPI_LROW); asm volatile("" : "+v"(rsv[ai][m]) :: "memory"); }
;     ...
; #pragma unroll
;         for (int r = 0; r < 8; ++r) { const int ai = r >> 2, m = r & 3; const int row = EPI_ROW; const float rs = rsv[ai][m];
;             f32x4 a0 = acc[ai][0][m][0] * rs + ba0, a1 = acc[ai][0][m][1] * rs + ba1, b0 = acc[ai][1][m][0] * rs + bb0, b1 = acc[ai][1][m][1] * rs + bb1;
;             bf16_t* rp = dst + (size_t)row * pitch;
;             if (mode == 1) { *(u32x4*)(rp + c0) = pack8(a0 * b0, a1 * b1); }
;             else if (mode == 3) {
; #pragma unroll
;                 for (int i = 0; i < 4; ++i) {
;                     const float ea0 = __expf(-a0[i]), ea1 = __expf(-a1[i]), eb0 = __expf(-b0[i]), eb1 = __expf(-b1[i]);
;                     a0[i] = (1.f + eb0) * __builtin_amdgcn_rcpf(1.f + ea0); a1[i] = (1.f + eb1) * __builtin_amdgcn_rcpf(1.f + ea1); b0[i] = __builtin_amdgcn_rcpf(1.f + eb0); b1[i] = __builtin_amdgcn_rcpf(1.f + eb1); }
;                 { const size_t po = (size_t)(row >> 1) * (2 * DM) + ((pn - 18) * 4 + wc) * 64 + (row & 1) * 32 + fq * 8;
;                   *(u32x4*)(SZC + po) = pack8(a0, a1); *(u32x4*)(SZA + po) = pack8(b0, b1); } }
;             else {
;                 if (mode == 2) { f32x4 cA, cB, sA, sB; ROPE_LOAD(cA, cB, sA, sB, r); const f32x4 x0 = a0, x1 = a1, y0 = b0, y1 = b1;
;                     a0 = x0 * cA - y0 * sA; a1 = x1 * cB - y1 * sB; b0 = y0 * cA + x0 * sA; b1 = y1 * cB + x1 * sB; }
;                 store_lines(stg + (wr * 4 + wc) * 1024, pack8(a0, a1), pack8(b0, b1), fr, fq, dst + (size_t)(row - fr) * pitch + (c0 - fq * 8), pitch); } }
.Lp4e_m0:
	v_mov_b32_e32 v202, 0x358637bd
	v_lshlrev_b32_e32 v146, 6, v1
	v_lshl_add_u32 v147, v201, 10, v146
	v_add_u32_e32 v147, s89, v147
	ds_read_b128 v[148:151], v147
	ds_read_b128 v[152:155], v147 offset:16
	ds_read_b128 v[156:159], v147 offset:32
	ds_read_b128 v[160:163], v147 offset:48
	ds_read_b128 v[230:233], v147 offset:8192
	ds_read_b128 v[234:237], v147 offset:8208
	ds_read_b128 v[238:241], v147 offset:8224
	ds_read_b128 v[242:245], v147 offset:8240
	s_mov_b32 s10, 11
	s_mov_b64 s[28:29], s[22:23]
	s_lshl_b32 s7, s6, 8
	s_cmp_lt_u32 s6, 4
	s_cbranch_scc1 .Lp4e_m0_go
	v_readlane_b32 s28, v254, 15
	v_readlane_b32 s29, v254, 16
	s_mov_b32 s7, 0
	s_mov_b32 s10, 9
.Lp4e_m0_go:
	s_nop 1
	s_add_i32 s7, s7, s83
	s_lshl_b32 s7, s7, 1
	s_lshl_b32 s31, s4, 8
	s_add_i32 s31, s31, s79
	s_lshl_b32 s5, s31, s10
	s_add_u32 s5, s5, s7
	s_add_u32 s28, s28, s5
	s_addc_u32 s29, s29, 0
	s_lshl_b32 s53, 8, s10
	s_add_i32 s55, s69, 0xc000
	s_lshr_b32 s9, s79, 4
	s_lshr_b32 s8, s80, 5
	s_add_u32 s9, s9, s8
	s_mov_b32 s8, 8
	v_lshrrev_b32_e32 v177, 3, v1
	v_lshlrev_b32_e32 v177, 13, v177
	v_and_b32_e32 v176, 7, v1
	v_lshl_add_u32 v177, v176, 7, v177
	v_lshl_add_u32 v177, v201, 4, v177
	v_add_u32_e32 v177, s55, v177
	v_lshl_add_u32 v186, v220, 4, s55
	v_lshrrev_b32_e32 v176, 3, v220
	v_lshlrev_b32_e32 v176, s10, v176
	v_and_b32_e32 v200, 7, v220
	v_lshl_add_u32 v176, v200, 4, v176
	s_waitcnt lgkmcnt(4)
	v_pk_add_f32 v[150:151], v[150:151], v[154:155]
	v_pk_add_f32 v[148:149], v[148:149], v[152:153]
	v_pk_add_f32 v[152:153], v[158:159], v[162:163]
	v_pk_add_f32 v[154:155], v[156:157], v[160:161]
	v_pk_add_f32 v[150:151], v[150:151], v[152:153]
	v_pk_add_f32 v[148:149], v[148:149], v[154:155]
	v_add_f32_e32 v148, v148, v149
	v_add_f32_e32 v150, v150, v151
	v_add_f32_e32 v148, v148, v150
	v_fmamk_f32 v148, v148, 0x3a800000, v202
	v_rsq_f32_e32 v148, v148
	s_waitcnt lgkmcnt(0)
	v_pk_add_f32 v[232:233], v[232:233], v[236:237]
	v_pk_add_f32 v[230:231], v[230:231], v[234:235]
	v_pk_add_f32 v[234:235], v[240:241], v[244:245]
	v_pk_add_f32 v[236:237], v[238:239], v[242:243]
	v_pk_add_f32 v[232:233], v[232:233], v[234:235]
	v_pk_add_f32 v[230:231], v[230:231], v[236:237]
	v_add_f32_e32 v230, v230, v231
	v_add_f32_e32 v232, v232, v233
	v_add_f32_e32 v230, v230, v232
	v_fmamk_f32 v230, v230, 0x3a800000, v202
	v_rsq_f32_e32 v230, v230
	v_lshlrev_b32_e32 v149, 2, v1
	v_add_u32_e32 v150, 0x40, v149
	v_add_u32_e32 v151, 0x80, v149
	v_add_u32_e32 v153, 0xc0, v149
	ds_bpermute_b32 v164, v149, v148
	ds_bpermute_b32 v166, v150, v148
	ds_bpermute_b32 v168, v151, v148
	ds_bpermute_b32 v170, v153, v148
	ds_bpermute_b32 v156, v149, v230
	ds_bpermute_b32 v158, v150, v230
	ds_bpermute_b32 v160, v151, v230
	ds_bpermute_b32 v162, v153, v230
	s_waitcnt lgkmcnt(0)
	s_cmp_eq_u32 s9, 1
	s_cbranch_scc1 .Lp4e_m0_rg1
	s_cmp_eq_u32 s9, 2
	s_cbranch_scc1 .Lp4e_m0_rg2
	s_cmp_eq_u32 s9, 3
	s_cbranch_scc1 .Lp4e_m0_rg3
	s_cmp_eq_u32 s9, 4
	s_cbranch_scc1 .Lp4e_m0_rg4
	s_cmp_eq_u32 s9, 5
	s_cbranch_scc1 .Lp4e_m0_rg5
	s_cmp_eq_u32 s9, 6
	s_cbranch_scc1 .Lp4e_m0_rg6
	s_cmp_eq_u32 s9, 7
	s_cbranch_scc1 .Lp4e_m0_rg7
.Lp4e_m0_rg0:
	s_lshl_b32 s52, 0, s10
	s_add_u32 s100, s28, s52
	s_addc_u32 s101, s29, 0
	s_add_u32 s98, s100, s53
	s_addc_u32 s99, s101, 0
	v_pk_fma_f32 v[142:143], v[142:143], v[164:165], v[54:55] op_sel_hi:[1,0,1]
	v_pk_fma_f32 v[144:145], v[144:145], v[164:165], v[56:57] op_sel_hi:[1,0,1]
	v_pk_fma_f32 v[138:139], v[138:139], v[164:165], v[50:51] op_sel_hi:[1,0,1]
	v_pk_fma_f32 v[140:141], v[140:141], v[164:165], v[52:53] op_sel_hi:[1,0,1]
	v_pk_fma_f32 v[134:135], v[134:135], v[164:165], v[46:47] op_sel_hi:[1,0,1]
	v_pk_fma_f32 v[136:137], v[136:137], v[164:165], v[48:49] op_sel_hi:[1,0,1]
	v_pk_fma_f32 v[130:131], v[130:131], v[164:165], v[42:43] op_sel_hi:[1,0,1]
	v_pk_fma_f32 v[132:133], v[132:133], v[164:165], v[44:45] op_sel_hi:[1,0,1]
	v_cvt_pk_bf16_f32 v172, v142, v143
	v_cvt_pk_bf16_f32 v173, v144, v145
	v_cvt_pk_bf16_f32 v174, v138, v139
	v_cvt_pk_bf16_f32 v175, v140, v141
	v_cvt_pk_bf16_f32 v196, v134, v135
	v_cvt_pk_bf16_f32 v197, v136, v137
	v_cvt_pk_bf16_f32 v198, v130, v131
	v_cvt_pk_bf16_f32 v199, v132, v133
	ds_write_b128 v177, v[172:175]
	ds_write_b128 v177, v[196:199] offset:64
	ds_read_b128 v[212:215], v186
	ds_read_b128 v[216:219], v186 offset:8192
	s_waitcnt lgkmcnt(1)
	global_store_dwordx4 v176, v[212:215], s[100:101]
	s_waitcnt lgkmcnt(0)
	global_store_dwordx4 v176, v[216:219], s[98:99]
	s_add_i32 s8, s8, -1
	s_cmp_eq_u32 s8, 0
	s_cbranch_scc1 .Lp4e_end
.Lp4e_m0_rg1:
	s_lshl_b32 s52, 16, s10
	s_add_u32 s100, s28, s52
	s_addc_u32 s101, s29, 0
	s_add_u32 s98, s100, s53
	s_addc_u32 s99, s101, 0
	v_pk_fma_f32 v[126:127], v[126:127], v[166:167], v[54:55] op_sel_hi:[1,0,1]
	v_pk_fma_f32 v[128:129], v[128:129], v[166:167], v[56:57] op_sel_hi:[1,0,1]
	v_pk_fma_f32 v[122:123], v[122:123], v[166:167], v[50:51] op_sel_hi:[1,0,1]
	v_pk_fma_f32 v[124:125], v[124:125], v[166:167], v[52:53] op_sel_hi:[1,0,1]
	v_pk_fma_f32 v[118:119], v[118:119], v[166:167], v[46:47] op_sel_hi:[1,0,1]
	v_pk_fma_f32 v[120:121], v[120:121], v[166:167], v[48:49] op_sel_hi:[1,0,1]
	v_pk_fma_f32 v[114:115], v[114:115], v[166:167], v[42:43] op_sel_hi:[1,0,1]
	v_pk_fma_f32 v[116:117], v[116:117], v[166:167], v[44:45] op_sel_hi:[1,0,1]
	v_cvt_pk_bf16_f32 v172, v126, v127
	v_cvt_pk_bf16_f32 v173, v128, v129
	v_cvt_pk_bf16_f32 v174, v122, v123
	v_cvt_pk_bf16_f32 v175, v124, v125
	v_cvt_pk_bf16_f32 v196, v118, v119
	v_cvt_pk_bf16_f32 v197, v120, v121
	v_cvt_pk_bf16_f32 v198, v114, v115
	v_cvt_pk_bf16_f32 v199, v116, v117
	ds_write_b128 v177, v[172:175]
	ds_write_b128 v177, v[196:199] offset:64
	ds_read_b128 v[212:215], v186
	ds_read_b128 v[216:219], v186 offset:8192
	s_waitcnt lgkmcnt(1)
	global_store_dwordx4 v176, v[212:215], s[100:101]
	s_waitcnt lgkmcnt(0)
	global_store_dwordx4 v176, v[216:219], s[98:99]
	s_add_i32 s8, s8, -1
	s_cmp_eq_u32 s8, 0
	s_cbranch_scc1 .Lp4e_end
; __device__ __forceinline__ u32x4 pack8(const f32x4 a, const f32x4 b) { u32x4 w; w.x = cvt_pk_bf16(a[0], a[1]); w.y = cvt_pk_bf16(a[2], a[3]); w.z = cvt_pk_bf16(b[0], b[1]); w.w = cvt_pk_bf16(b[2], b[3]); return w; }
; #define ROPE_LOAD(C0, C1, S0, S1, r_) do { const int pos_ = (u.pm * BM + ((r_) >> 2) * HALF + wr * 64 + ((r_) & 3) * 16 + fr) & (SEQ - 1); const float* cp_ = cosT + pos_ * 32 + fq * 8; const float* sp_ = sinT + pos_ * 32 + fq * 8; \
;             C0 = *(const f32x4*)cp_; C1 = *(const f32x4*)(cp_ + 4); S0 = *(const f32x4*)sp_; S1 = *(const f32x4*)(sp_ + 4); } while (0)
;     __device__ __forceinline__ void operator()(const f32x4 (&acc)[2][2][4][2], const Unit& u, int wr, int wc, int fr, int fq) const {
;     ...
;         for (int r = 0; r < 8; ++r) { const int ai = r >> 2, m = r & 3; const int row = EPI_ROW; const float rs = rsv[ai][m];
;             f32x4 a0 = acc[ai][0][m][0] * rs + ba0, a1 = acc[ai][0][m][1] * rs + ba1, b0 = acc[ai][1][m][0] * rs + bb0, b1 = acc[ai][1][m][1] * rs + bb1;
;             bf16_t* rp = dst + (size_t)row * pitch;
;             if (mode == 1) { *(u32x4*)(rp + c0) = pack8(a0 * b0, a1 * b1); }
;             else if (mode == 3) {
; #pragma unroll
;                 for (int i = 0; i < 4; ++i) {
;                     const float ea0 = __expf(-a0[i]), ea1 = __expf(-a1[i]), eb0 = __expf(-b0[i]), eb1 = __expf(-b1[i]);
;                     a0[i] = (1.f + eb0) * __builtin_amdgcn_rcpf(1.f + ea0); a1[i] = (1.f + eb1) * __builtin_amdgcn_rcpf(1.f + ea1); b0[i] = __builtin_amdgcn_rcpf(1.f + eb0); b1[i] = __builtin_amdgcn_rcpf(1.f + eb1); }
;                 { const size_t po = (size_t)(row >> 1) * (2 * DM) + ((pn - 18) * 4 + wc) * 64 + (row & 1) * 32 + fq * 8;
;                   *(u32x4*)(SZC + po) = pack8(a0, a1); *(u32x4*)(SZA + po) = pack8(b0, b1); } }
;             else {
;                 if (mode == 2) { f32x4 cA, cB, sA, sB; ROPE_LOAD(cA, cB, sA, sB, r); const f32x4 x0 = a0, x1 = a1, y0 = b0, y1 = b1;
;                     a0 = x0 * cA - y0 * sA; a1 = x1 * cB - y1 * sB; b0 = y0 * cA + x0 * sA; b1 = y1 * cB + x1 * sB; }
;                 store_lines(stg + (wr * 4 + wc) * 1024, pack8(a0, a1), pack8(b0, b1), fr, fq, dst + (size_t)(row - fr) * pitch + (c0 - fq * 8), pitch); } }
.Lp4e_m0_rg2:
	s_lshl_b32 s52, 32, s10
	s_add_u32 s100, s28, s52
	s_addc_u32 s101, s29, 0
	s_add_u32 s98, s100, s53
	s_addc_u32 s99, s101, 0
	v_pk_fma_f32 v[110:111], v[110:111], v[168:169], v[54:55] op_sel_hi:[1,0,1]
	v_pk_fma_f32 v[112:113], v[112:113], v[168:169], v[56:57] op_sel_hi:[1,0,1]
	v_pk_fma_f32 v[106:107], v[106:107], v[168:169], v[50:51] op_sel_hi:[1,0,1]
	v_pk_fma_f32 v[108:109], v[108:109], v[168:169], v[52:53] op_sel_hi:[1,0,1]
	v_pk_fma_f32 v[102:103], v[102:103], v[168:169], v[46:47] op_sel_hi:[1,0,1]
	v_pk_fma_f32 v[104:105], v[104:105], v[168:169], v[48:49] op_sel_hi:[1,0,1]
	v_pk_fma_f32 v[98:99], v[98:99], v[168:169], v[42:43] op_sel_hi:[1,0,1]
	v_pk_fma_f32 v[100:101], v[100:101], v[168:169], v[44:45] op_sel_hi:[1,0,1]
	v_cvt_pk_bf16_f32 v172, v110, v111
	v_cvt_pk_bf16_f32 v173, v112, v113
	v_cvt_pk_bf16_f32 v174, v106, v107
	v_cvt_pk_bf16_f32 v175, v108, v109
	v_cvt_pk_bf16_f32 v196, v102, v103
	v_cvt_pk_bf16_f32 v197, v104, v105
	v_cvt_pk_bf16_f32 v198, v98, v99
	v_cvt_pk_bf16_f32 v199, v100, v101
	ds_write_b128 v177, v[172:175]
	ds_write_b128 v177, v[196:199] offset:64
	ds_read_b128 v[212:215], v186
	ds_read_b128 v[216:219], v186 offset:8192
	s_waitcnt lgkmcnt(1)
	global_store_dwordx4 v176, v[212:215], s[100:101]
	s_waitcnt lgkmcnt(0)
	global_store_dwordx4 v176, v[216:219], s[98:99]
	s_add_i32 s8, s8, -1
	s_cmp_eq_u32 s8, 0
	s_cbranch_scc1 .Lp4e_end
.Lp4e_m0_rg3:
	s_lshl_b32 s52, 48, s10
	s_add_u32 s100, s28, s52
	s_addc_u32 s101, s29, 0
	s_add_u32 s98, s100, s53
	s_addc_u32 s99, s101, 0
	v_pk_fma_f32 v[94:95], v[94:95], v[170:171], v[54:55] op_sel_hi:[1,0,1]
	v_pk_fma_f32 v[96:97], v[96:97], v[170:171], v[56:57] op_sel_hi:[1,0,1]
	v_pk_fma_f32 v[90:91], v[90:91], v[170:171], v[50:51] op_sel_hi:[1,0,1]
	v_pk_fma_f32 v[92:93], v[92:93], v[170:171], v[52:53] op_sel_hi:[1,0,1]
	v_pk_fma_f32 v[86:87], v[86:87], v[170:171], v[46:47] op_sel_hi:[1,0,1]
	v_pk_fma_f32 v[88:89], v[88:89], v[170:171], v[48:49] op_sel_hi:[1,0,1]
	v_pk_fma_f32 v[82:83], v[82:83], v[170:171], v[42:43] op_sel_hi:[1,0,1]
	v_pk_fma_f32 v[84:85], v[84:85], v[170:171], v[44:45] op_sel_hi:[1,0,1]
	v_cvt_pk_bf16_f32 v172, v94, v95
	v_cvt_pk_bf16_f32 v173, v96, v97
	v_cvt_pk_bf16_f32 v174, v90, v91
	v_cvt_pk_bf16_f32 v175, v92, v93
	v_cvt_pk_bf16_f32 v196, v86, v87
	v_cvt_pk_bf16_f32 v197, v88, v89
	v_cvt_pk_bf16_f32 v198, v82, v83
	v_cvt_pk_bf16_f32 v199, v84, v85
	ds_write_b128 v177, v[172:175]
	ds_write_b128 v177, v[196:199] offset:64
	ds_read_b128 v[212:215], v186
	ds_read_b128 v[216:219], v186 offset:8192
	s_waitcnt lgkmcnt(1)
	global_store_dwordx4 v176, v[212:215], s[100:101]
	s_waitcnt lgkmcnt(0)
	global_store_dwordx4 v176, v[216:219], s[98:99]
	s_add_i32 s8, s8, -1
	s_cmp_eq_u32 s8, 0
	s_cbranch_scc1 .Lp4e_end
.Lp4e_m0_rg4:
	s_lshl_b32 s52, 128, s10
	s_add_u32 s100, s28, s52
	s_addc_u32 s101, s29, 0
	s_add_u32 s98, s100, s53
	s_addc_u32 s99, s101, 0
	v_pk_fma_f32 v[78:79], v[78:79], v[156:157], v[54:55] op_sel_hi:[1,0,1]
	v_pk_fma_f32 v[80:81], v[80:81], v[156:157], v[56:57] op_sel_hi:[1,0,1]
	v_pk_fma_f32 v[74:75], v[74:75], v[156:157], v[50:51] op_sel_hi:[1,0,1]
	v_pk_fma_f32 v[76:77], v[76:77], v[156:157], v[52:53] op_sel_hi:[1,0,1]
	v_pk_fma_f32 v[70:71], v[70:71], v[156:157], v[46:47] op_sel_hi:[1,0,1]
	v_pk_fma_f32 v[72:73], v[72:73], v[156:157], v[48:49] op_sel_hi:[1,0,1]
	v_pk_fma_f32 v[66:67], v[66:67], v[156:157], v[42:43] op_sel_hi:[1,0,1]
	v_pk_fma_f32 v[68:69], v[68:69], v[156:157], v[44:45] op_sel_hi:[1,0,1]
	v_cvt_pk_bf16_f32 v172, v78, v79
	v_cvt_pk_bf16_f32 v173, v80, v81
	v_cvt_pk_bf16_f32 v174, v74, v75
	v_cvt_pk_bf16_f32 v175, v76, v77
	v_cvt_pk_bf16_f32 v196, v70, v71
	v_cvt_pk_bf16_f32 v197, v72, v73
	v_cvt_pk_bf16_f32 v198, v66, v67
	v_cvt_pk_bf16_f32 v199, v68, v69
	ds_write_b128 v177, v[172:175]
	ds_write_b128 v177, v[196:199] offset:64
	ds_read_b128 v[212:215], v186
	ds_read_b128 v[216:219], v186 offset:8192
	s_waitcnt lgkmcnt(1)
	global_store_dwordx4 v176, v[212:215], s[100:101]
	s_waitcnt lgkmcnt(0)
	global_store_dwordx4 v176, v[216:219], s[98:99]
	s_add_i32 s8, s8, -1
	s_cmp_eq_u32 s8, 0
	s_cbranch_scc1 .Lp4e_end
.Lp4e_m0_rg5:
	s_lshl_b32 s52, 144, s10
	s_add_u32 s100, s28, s52
	s_addc_u32 s101, s29, 0
	s_add_u32 s98, s100, s53
	s_addc_u32 s99, s101, 0
	v_pk_fma_f32 v[62:63], v[62:63], v[158:159], v[54:55] op_sel_hi:[1,0,1]
	v_pk_fma_f32 v[64:65], v[64:65], v[158:159], v[56:57] op_sel_hi:[1,0,1]
	v_pk_fma_f32 v[58:59], v[58:59], v[158:159], v[50:51] op_sel_hi:[1,0,1]
	v_pk_fma_f32 v[60:61], v[60:61], v[158:159], v[52:53] op_sel_hi:[1,0,1]
	v_pk_fma_f32 v[38:39], v[38:39], v[158:159], v[46:47] op_sel_hi:[1,0,1]
	v_pk_fma_f32 v[40:41], v[40:41], v[158:159], v[48:49] op_sel_hi:[1,0,1]
	v_pk_fma_f32 v[34:35], v[34:35], v[158:159], v[42:43] op_sel_hi:[1,0,1]
	v_pk_fma_f32 v[36:37], v[36:37], v[158:159], v[44:45] op_sel_hi:[1,0,1]
	v_cvt_pk_bf16_f32 v172, v62, v63
	v_cvt_pk_bf16_f32 v173, v64, v65
	v_cvt_pk_bf16_f32 v174, v58, v59
	v_cvt_pk_bf16_f32 v175, v60, v61
	v_cvt_pk_bf16_f32 v196, v38, v39
	v_cvt_pk_bf16_f32 v197, v40, v41
	v_cvt_pk_bf16_f32 v198, v34, v35
	v_cvt_pk_bf16_f32 v199, v36, v37
	ds_write_b128 v177, v[172:175]
	ds_write_b128 v177, v[196:199] offset:64
	ds_read_b128 v[212:215], v186
	ds_read_b128 v[216:219], v186 offset:8192
	s_waitcnt lgkmcnt(1)
	global_store_dwordx4 v176, v[212:215], s[100:101]
	s_waitcnt lgkmcnt(0)
	global_store_dwordx4 v176, v[216:219], s[98:99]
	s_add_i32 s8, s8, -1
	s_cmp_eq_u32 s8, 0
	s_cbranch_scc1 .Lp4e_end
; __device__ __forceinline__ u32x4 pack8(const f32x4 a, const f32x4 b) { u32x4 w; w.x = cvt_pk_bf16(a[0], a[1]); w.y = cvt_pk_bf16(a[2], a[3]); w.z = cvt_pk_bf16(b[0], b[1]); w.w = cvt_pk_bf16(b[2], b[3]); return w; }
; #define ROPE_LOAD(C0, C1, S0, S1, r_) do { const int pos_ = (u.pm * BM + ((r_) >> 2) * HALF + wr * 64 + ((r_) & 3) * 16 + fr) & (SEQ - 1); const float* cp_ = cosT + pos_ * 32 + fq * 8; const float* sp_ = sinT + pos_ * 32 + fq * 8; \
;             C0 = *(const f32x4*)cp_; C1 = *(const f32x4*)(cp_ + 4); S0 = *(const f32x4*)sp_; S1 = *(const f32x4*)(sp_ + 4); } while (0)
;     __device__ __forceinline__ void operator()(const f32x4 (&acc)[2][2][4][2], const Unit& u, int wr, int wc, int fr, int fq) const {
;     ...
; #pragma unroll
;         for (int r = 0; r < 8; ++r) { const int ai = r >> 2, m = r & 3; const int row = EPI_ROW; const float rs = rsv[ai][m];
;             f32x4 a0 = acc[ai][0][m][0] * rs + ba0, a1 = acc[ai][0][m][1] * rs + ba1, b0 = acc[ai][1][m][0] * rs + bb0, b1 = acc[ai][1][m][1] * rs + bb1;
;             bf16_t* rp = dst + (size_t)row * pitch;
;             if (mode == 1) { *(u32x4*)(rp + c0) = pack8(a0 * b0, a1 * b1); }
;             else if (mode == 3) {
; #pragma unroll
;                 for (int i = 0; i < 4; ++i) {
;                     const float ea0 = __expf(-a0[i]), ea1 = __expf(-a1[i]), eb0 = __expf(-b0[i]), eb1 = __expf(-b1[i]);
;                     a0[i] = (1.f + eb0) * __builtin_amdgcn_rcpf(1.f + ea0); a1[i] = (1.f + eb1) * __builtin_amdgcn_rcpf(1.f + ea1); b0[i] = __builtin_amdgcn_rcpf(1.f + eb0); b1[i] = __builtin_amdgcn_rcpf(1.f + eb1); }
;                 { const size_t po = (size_t)(row >> 1) * (2 * DM) + ((pn - 18) * 4 + wc) * 64 + (row & 1) * 32 + fq * 8;
;                   *(u32x4*)(SZC + po) = pack8(a0, a1); *(u32x4*)(SZA + po) = pack8(b0, b1); } }
;             else {
;                 if (mode == 2) { f32x4 cA, cB, sA, sB; ROPE_LOAD(cA, cB, sA, sB, r); const f32x4 x0 = a0, x1 = a1, y0 = b0, y1 = b1;
;                     a0 = x0 * cA - y0 * sA; a1 = x1 * cB - y1 * sB; b0 = y0 * cA + x0 * sA; b1 = y1 * cB + x1 * sB; }
;                 store_lines(stg + (wr * 4 + wc) * 1024, pack8(a0, a1), pack8(b0, b1), fr, fq, dst + (size_t)(row - fr) * pitch + (c0 - fq * 8), pitch); } }
.Lp4e_m0_rg6:
	s_lshl_b32 s52, 160, s10
	s_add_u32 s100, s28, s52
	s_addc_u32 s101, s29, 0
	s_add_u32 s98, s100, s53
	s_addc_u32 s99, s101, 0
	v_pk_fma_f32 v[30:31], v[30:31], v[160:161], v[54:55] op_sel_hi:[1,0,1]
	v_pk_fma_f32 v[32:33], v[32:33], v[160:161], v[56:57] op_sel_hi:[1,0,1]
	v_pk_fma_f32 v[26:27], v[26:27], v[160:161], v[50:51] op_sel_hi:[1,0,1]
	v_pk_fma_f32 v[28:29], v[28:29], v[160:161], v[52:53] op_sel_hi:[1,0,1]
	v_pk_fma_f32 v[22:23], v[22:23], v[160:161], v[46:47] op_sel_hi:[1,0,1]
	v_pk_fma_f32 v[24:25], v[24:25], v[160:161], v[48:49] op_sel_hi:[1,0,1]
	v_pk_fma_f32 v[18:19], v[18:19], v[160:161], v[42:43] op_sel_hi:[1,0,1]
	v_pk_fma_f32 v[20:21], v[20:21], v[160:161], v[44:45] op_sel_hi:[1,0,1]
	v_cvt_pk_bf16_f32 v172, v30, v31
	v_cvt_pk_bf16_f32 v173, v32, v33
	v_cvt_pk_bf16_f32 v174, v26, v27
	v_cvt_pk_bf16_f32 v175, v28, v29
	v_cvt_pk_bf16_f32 v196, v22, v23
	v_cvt_pk_bf16_f32 v197, v24, v25
	v_cvt_pk_bf16_f32 v198, v18, v19
	v_cvt_pk_bf16_f32 v199, v20, v21
	ds_write_b128 v177, v[172:175]
	ds_write_b128 v177, v[196:199] offset:64
	ds_read_b128 v[212:215], v186
	ds_read_b128 v[216:219], v186 offset:8192
	s_waitcnt lgkmcnt(1)
	global_store_dwordx4 v176, v[212:215], s[100:101]
	s_waitcnt lgkmcnt(0)
	global_store_dwordx4 v176, v[216:219], s[98:99]
	s_add_i32 s8, s8, -1
	s_cmp_eq_u32 s8, 0
	s_cbranch_scc1 .Lp4e_end
.Lp4e_m0_rg7:
	s_lshl_b32 s52, 176, s10
	s_add_u32 s100, s28, s52
	s_addc_u32 s101, s29, 0
	s_add_u32 s98, s100, s53
	s_addc_u32 s99, s101, 0
	v_pk_fma_f32 v[14:15], v[14:15], v[162:163], v[54:55] op_sel_hi:[1,0,1]
	v_pk_fma_f32 v[16:17], v[16:17], v[162:163], v[56:57] op_sel_hi:[1,0,1]
	v_pk_fma_f32 v[10:11], v[10:11], v[162:163], v[50:51] op_sel_hi:[1,0,1]
	v_pk_fma_f32 v[12:13], v[12:13], v[162:163], v[52:53] op_sel_hi:[1,0,1]
	v_pk_fma_f32 v[6:7], v[6:7], v[162:163], v[46:47] op_sel_hi:[1,0,1]
	v_pk_fma_f32 v[8:9], v[8:9], v[162:163], v[48:49] op_sel_hi:[1,0,1]
	v_pk_fma_f32 v[2:3], v[2:3], v[162:163], v[42:43] op_sel_hi:[1,0,1]
	v_pk_fma_f32 v[4:5], v[4:5], v[162:163], v[44:45] op_sel_hi:[1,0,1]
	v_cvt_pk_bf16_f32 v172, v14, v15
	v_cvt_pk_bf16_f32 v173, v16, v17
	v_cvt_pk_bf16_f32 v174, v10, v11
	v_cvt_pk_bf16_f32 v175, v12, v13
	v_cvt_pk_bf16_f32 v196, v6, v7
	v_cvt_pk_bf16_f32 v197, v8, v9
	v_cvt_pk_bf16_f32 v198, v2, v3
	v_cvt_pk_bf16_f32 v199, v4, v5
	ds_write_b128 v177, v[172:175]
	ds_write_b128 v177, v[196:199] offset:64
	ds_read_b128 v[212:215], v186
	ds_read_b128 v[216:219], v186 offset:8192
	s_waitcnt lgkmcnt(1)
	global_store_dwordx4 v176, v[212:215], s[100:101]
	s_waitcnt lgkmcnt(0)
	global_store_dwordx4 v176, v[216:219], s[98:99]
	s_add_i32 s8, s8, -1
	s_cmp_eq_u32 s8, 0
	s_cbranch_scc1 .Lp4e_end
	s_branch .Lp4e_m0_rg0
.Lp4e_m2:
	v_mov_b32_e32 v202, 0x358637bd
	v_lshlrev_b32_e32 v146, 6, v1
	v_lshl_add_u32 v147, v201, 10, v146
	v_add_u32_e32 v147, s89, v147
	ds_read_b128 v[148:151], v147
	ds_read_b128 v[152:155], v147 offset:16
	ds_read_b128 v[156:159], v147 offset:32
	ds_read_b128 v[160:163], v147 offset:48
	ds_read_b128 v[230:233], v147 offset:8192
	ds_read_b128 v[234:237], v147 offset:8208
	ds_read_b128 v[238:241], v147 offset:8224
	ds_read_b128 v[242:245], v147 offset:8240
	s_mov_b32 s10, 11
	s_mov_b64 s[28:29], s[26:27]
	s_add_i32 s7, s6, -12
	s_lshl_b32 s7, s7, 8
	s_cmp_lt_u32 s6, 16
	s_cbranch_scc1 .Lp4e_m2_go
	v_readlane_b32 s28, v254, 13
	v_readlane_b32 s29, v254, 14
	s_mov_b32 s7, 0
	s_mov_b32 s10, 9
.Lp4e_m2_go:
	s_nop 1
	s_add_i32 s7, s7, s83
	s_lshl_b32 s7, s7, 1
	s_lshl_b32 s31, s4, 8
	s_add_i32 s31, s31, s79
	s_lshl_b32 s5, s31, s10
	s_add_u32 s5, s5, s7
	s_add_u32 s28, s28, s5
	s_addc_u32 s29, s29, 0
	s_lshl_b32 s53, 8, s10
	s_add_i32 s55, s69, 0xc000
	s_lshr_b32 s9, s79, 4
	s_lshr_b32 s8, s80, 5
	s_add_u32 s9, s9, s8
	s_mov_b32 s8, 8
	v_lshrrev_b32_e32 v177, 3, v1
	v_lshlrev_b32_e32 v177, 13, v177
	v_and_b32_e32 v176, 7, v1
	v_lshl_add_u32 v177, v176, 7, v177
	v_lshl_add_u32 v177, v201, 4, v177
	v_add_u32_e32 v177, s55, v177
	v_lshl_add_u32 v186, v220, 4, s55
	v_lshrrev_b32_e32 v176, 3, v220
	v_lshlrev_b32_e32 v176, s10, v176
	v_and_b32_e32 v200, 7, v220
	v_lshl_add_u32 v176, v200, 4, v176
	v_lshlrev_b32_e32 v200, 7, v1
	v_lshl_add_u32 v200, v201, 5, v200
	s_waitcnt lgkmcnt(4)
	v_pk_add_f32 v[150:151], v[150:151], v[154:155]
	v_pk_add_f32 v[148:149], v[148:149], v[152:153]
	v_pk_add_f32 v[152:153], v[158:159], v[162:163]
	v_pk_add_f32 v[154:155], v[156:157], v[160:161]
	v_pk_add_f32 v[150:151], v[150:151], v[152:153]
	v_pk_add_f32 v[148:149], v[148:149], v[154:155]
	v_add_f32_e32 v148, v148, v149
	v_add_f32_e32 v150, v150, v151
	v_add_f32_e32 v148, v148, v150
	v_fmamk_f32 v148, v148, 0x3a800000, v202
	v_rsq_f32_e32 v148, v148
	s_waitcnt lgkmcnt(0)
	v_pk_add_f32 v[232:233], v[232:233], v[236:237]
	v_pk_add_f32 v[230:231], v[230:231], v[234:235]
	v_pk_add_f32 v[234:235], v[240:241], v[244:245]
	v_pk_add_f32 v[236:237], v[238:239], v[242:243]
	v_pk_add_f32 v[232:233], v[232:233], v[234:235]
	v_pk_add_f32 v[230:231], v[230:231], v[236:237]
	v_add_f32_e32 v230, v230, v231
	v_add_f32_e32 v232, v232, v233
	v_add_f32_e32 v230, v230, v232
	v_fmamk_f32 v230, v230, 0x3a800000, v202
	v_rsq_f32_e32 v230, v230
	v_lshlrev_b32_e32 v149, 2, v1
	v_add_u32_e32 v150, 0x40, v149
	v_add_u32_e32 v151, 0x80, v149
	v_add_u32_e32 v153, 0xc0, v149
	ds_bpermute_b32 v164, v149, v148
	ds_bpermute_b32 v166, v150, v148
	ds_bpermute_b32 v168, v151, v148
	ds_bpermute_b32 v170, v153, v148
	ds_bpermute_b32 v156, v149, v230
	ds_bpermute_b32 v158, v150, v230
	ds_bpermute_b32 v160, v151, v230
	ds_bpermute_b32 v162, v153, v230
	s_waitcnt lgkmcnt(0)
	s_lshr_b32 s54, s9, 2
	s_lshl_b32 s54, s54, 7
	s_and_b32 s5, s9, 3
	s_lshl_b32 s5, s5, 4
	s_add_i32 s54, s54, s5
	s_bitcmp1_b32 s9, 0
	s_cbranch_scc1 .Lp4e_m2_odd
	s_add_i32 s54, s31, s54
	s_and_b32 s54, s54, 0x1fff
	s_lshl_b32 s54, s54, 7
	s_add_u32 s56, s18, s54
	s_addc_u32 s57, s19, 0
	s_add_u32 s58, s20, s54
	s_addc_u32 s59, s21, 0
	global_load_dwordx4 v[230:233], v200, s[56:57]
	global_load_dwordx4 v[234:237], v200, s[56:57] offset:16
	global_load_dwordx4 v[238:241], v200, s[58:59]
	global_load_dwordx4 v[242:245], v200, s[58:59] offset:16
	s_branch .Lp4e_m2_disp
; __device__ __forceinline__ u32x4 pack8(const f32x4 a, const f32x4 b) { u32x4 w; w.x = cvt_pk_bf16(a[0], a[1]); w.y = cvt_pk_bf16(a[2], a[3]); w.z = cvt_pk_bf16(b[0], b[1]); w.w = cvt_pk_bf16(b[2], b[3]); return w; }
; #define ROPE_LOAD(C0, C1, S0, S1, r_) do { const int pos_ = (u.pm * BM + ((r_) >> 2) * HALF + wr * 64 + ((r_) & 3) * 16 + fr) & (SEQ - 1); const float* cp_ = cosT + pos_ * 32 + fq * 8; const float* sp_ = sinT + pos_ * 32 + fq * 8; \
;             C0 = *(const f32x4*)cp_; C1 = *(const f32x4*)(cp_ + 4); S0 = *(const f32x4*)sp_; S1 = *(const f32x4*)(sp_ + 4); } while (0)
;     __device__ __forceinline__ void operator()(const f32x4 (&acc)[2][2][4][2], const Unit& u, int wr, int wc, int fr, int fq) const {
;     ...
; #pragma unroll
;         for (int r = 0; r < 8; ++r) { const int ai = r >> 2, m = r & 3; const int row = EPI_ROW; const float rs = rsv[ai][m];
;             f32x4 a0 = acc[ai][0][m][0] * rs + ba0, a1 = acc[ai][0][m][1] * rs + ba1, b0 = acc[ai][1][m][0] * rs + bb0, b1 = acc[ai][1][m][1] * rs + bb1;
;             bf16_t* rp = dst + (size_t)row * pitch;
;             if (mode == 1) { *(u32x4*)(rp + c0) = pack8(a0 * b0, a1 * b1); }
;             else if (mode == 3) {
; #pragma unroll
;                 for (int i = 0; i < 4; ++i) {
;                     const float ea0 = __expf(-a0[i]), ea1 = __expf(-a1[i]), eb0 = __expf(-b0[i]), eb1 = __expf(-b1[i]);
;                     a0[i] = (1.f + eb0) * __builtin_amdgcn_rcpf(1.f + ea0); a1[i] = (1.f + eb1) * __builtin_amdgcn_rcpf(1.f + ea1); b0[i] = __builtin_amdgcn_rcpf(1.f + eb0); b1[i] = __builtin_amdgcn_rcpf(1.f + eb1); }
;                 { const size_t po = (size_t)(row >> 1) * (2 * DM) + ((pn - 18) * 4 + wc) * 64 + (row & 1) * 32 + fq * 8;
;                   *(u32x4*)(SZC + po) = pack8(a0, a1); *(u32x4*)(SZA + po) = pack8(b0, b1); } }
;             else {
;                 if (mode == 2) { f32x4 cA, cB, sA, sB; ROPE_LOAD(cA, cB, sA, sB, r); const f32x4 x0 = a0, x1 = a1, y0 = b0, y1 = b1;
;                     a0 = x0 * cA - y0 * sA; a1 = x1 * cB - y1 * sB; b0 = y0 * cA + x0 * sA; b1 = y1 * cB + x1 * sB; }
;                 store_lines(stg + (wr * 4 + wc) * 1024, pack8(a0, a1), pack8(b0, b1), fr, fq, dst + (size_t)(row - fr) * pitch + (c0 - fq * 8), pitch); } }
.Lp4e_m2_odd:
	s_add_i32 s54, s31, s54
	s_and_b32 s54, s54, 0x1fff
	s_lshl_b32 s54, s54, 7
	s_add_u32 s56, s18, s54
	s_addc_u32 s57, s19, 0
	s_add_u32 s58, s20, s54
	s_addc_u32 s59, s21, 0
	global_load_dwordx4 v[222:225], v200, s[56:57]
	global_load_dwordx4 v[246:249], v200, s[56:57] offset:16
	global_load_dwordx4 v[148:151], v200, s[58:59]
	global_load_dwordx4 v[152:155], v200, s[58:59] offset:16
.Lp4e_m2_disp:
	s_cmp_eq_u32 s9, 1
	s_cbranch_scc1 .Lp4e_m2_rg1
	s_cmp_eq_u32 s9, 2
	s_cbranch_scc1 .Lp4e_m2_rg2
	s_cmp_eq_u32 s9, 3
	s_cbranch_scc1 .Lp4e_m2_rg3
	s_cmp_eq_u32 s9, 4
	s_cbranch_scc1 .Lp4e_m2_rg4
	s_cmp_eq_u32 s9, 5
	s_cbranch_scc1 .Lp4e_m2_rg5
	s_cmp_eq_u32 s9, 6
	s_cbranch_scc1 .Lp4e_m2_rg6
	s_cmp_eq_u32 s9, 7
	s_cbranch_scc1 .Lp4e_m2_rg7
.Lp4e_m2_rg0:
	s_lshl_b32 s52, 0, s10
	s_add_u32 s100, s28, s52
	s_addc_u32 s101, s29, 0
	s_add_u32 s98, s100, s53
	s_addc_u32 s99, s101, 0
	s_cmp_eq_u32 s8, 1
	s_cbranch_scc1 .Lp4e_m2_n0
	s_movk_i32 s54, 0x10
	s_add_i32 s54, s31, s54
	s_and_b32 s54, s54, 0x1fff
	s_lshl_b32 s54, s54, 7
	s_add_u32 s56, s18, s54
	s_addc_u32 s57, s19, 0
	s_add_u32 s58, s20, s54
	s_addc_u32 s59, s21, 0
	global_load_dwordx4 v[222:225], v200, s[56:57]
	global_load_dwordx4 v[246:249], v200, s[56:57] offset:16
	global_load_dwordx4 v[148:151], v200, s[58:59]
	global_load_dwordx4 v[152:155], v200, s[58:59] offset:16
.Lp4e_m2_n0:
	v_pk_fma_f32 v[142:143], v[142:143], v[164:165], v[54:55] op_sel_hi:[1,0,1]
	v_pk_fma_f32 v[144:145], v[144:145], v[164:165], v[56:57] op_sel_hi:[1,0,1]
	v_pk_fma_f32 v[138:139], v[138:139], v[164:165], v[50:51] op_sel_hi:[1,0,1]
	v_pk_fma_f32 v[140:141], v[140:141], v[164:165], v[52:53] op_sel_hi:[1,0,1]
	v_pk_fma_f32 v[134:135], v[134:135], v[164:165], v[46:47] op_sel_hi:[1,0,1]
	v_pk_fma_f32 v[136:137], v[136:137], v[164:165], v[48:49] op_sel_hi:[1,0,1]
	v_pk_fma_f32 v[130:131], v[130:131], v[164:165], v[42:43] op_sel_hi:[1,0,1]
	v_pk_fma_f32 v[132:133], v[132:133], v[164:165], v[44:45] op_sel_hi:[1,0,1]
	s_cmp_lg_u32 s8, 8
	s_cbranch_scc1 .Lp4e_m2_w0
	s_waitcnt vmcnt(4)
.Lp4e_m2_w0:
	s_cmp_lg_u32 s8, 1
	s_cbranch_scc1 .Lp4e_m2_v0
	s_waitcnt vmcnt(2)
.Lp4e_m2_v0:
	s_waitcnt vmcnt(6)
	v_pk_mul_f32 v[212:213], v[134:135], v[238:239]
	v_pk_mul_f32 v[214:215], v[136:137], v[240:241]
	v_pk_mul_f32 v[216:217], v[130:131], v[242:243]
	v_pk_mul_f32 v[218:219], v[132:133], v[244:245]
	v_pk_fma_f32 v[212:213], v[142:143], v[230:231], v[212:213] neg_lo:[0,0,1] neg_hi:[0,0,1]
	v_pk_fma_f32 v[214:215], v[144:145], v[232:233], v[214:215] neg_lo:[0,0,1] neg_hi:[0,0,1]
	v_pk_fma_f32 v[216:217], v[138:139], v[234:235], v[216:217] neg_lo:[0,0,1] neg_hi:[0,0,1]
	v_pk_fma_f32 v[218:219], v[140:141], v[236:237], v[218:219] neg_lo:[0,0,1] neg_hi:[0,0,1]
	v_pk_mul_f32 v[142:143], v[142:143], v[238:239]
	v_pk_mul_f32 v[144:145], v[144:145], v[240:241]
	v_pk_mul_f32 v[138:139], v[138:139], v[242:243]
	v_pk_mul_f32 v[140:141], v[140:141], v[244:245]
	v_pk_fma_f32 v[134:135], v[134:135], v[230:231], v[142:143]
	v_pk_fma_f32 v[136:137], v[136:137], v[232:233], v[144:145]
	v_pk_fma_f32 v[130:131], v[130:131], v[234:235], v[138:139]
	v_pk_fma_f32 v[132:133], v[132:133], v[236:237], v[140:141]
	v_cvt_pk_bf16_f32 v172, v212, v213
	v_cvt_pk_bf16_f32 v173, v214, v215
	v_cvt_pk_bf16_f32 v174, v216, v217
	v_cvt_pk_bf16_f32 v175, v218, v219
	v_cvt_pk_bf16_f32 v196, v134, v135
	v_cvt_pk_bf16_f32 v197, v136, v137
	v_cvt_pk_bf16_f32 v198, v130, v131
	v_cvt_pk_bf16_f32 v199, v132, v133
	ds_write_b128 v177, v[172:175]
	ds_write_b128 v177, v[196:199] offset:64
	ds_read_b128 v[212:215], v186
	ds_read_b128 v[216:219], v186 offset:8192
	s_waitcnt lgkmcnt(1)
	global_store_dwordx4 v176, v[212:215], s[100:101]
	s_waitcnt lgkmcnt(0)
	global_store_dwordx4 v176, v[216:219], s[98:99]
	s_add_i32 s8, s8, -1
	s_cmp_eq_u32 s8, 0
	s_cbranch_scc1 .Lp4e_end
.Lp4e_m2_rg1:
	s_lshl_b32 s52, 16, s10
	s_add_u32 s100, s28, s52
	s_addc_u32 s101, s29, 0
	s_add_u32 s98, s100, s53
	s_addc_u32 s99, s101, 0
	s_cmp_eq_u32 s8, 1
	s_cbranch_scc1 .Lp4e_m2_n1
	s_movk_i32 s54, 0x20
	s_add_i32 s54, s31, s54
	s_and_b32 s54, s54, 0x1fff
	s_lshl_b32 s54, s54, 7
	s_add_u32 s56, s18, s54
	s_addc_u32 s57, s19, 0
	s_add_u32 s58, s20, s54
	s_addc_u32 s59, s21, 0
	global_load_dwordx4 v[230:233], v200, s[56:57]
	global_load_dwordx4 v[234:237], v200, s[56:57] offset:16
	global_load_dwordx4 v[238:241], v200, s[58:59]
	global_load_dwordx4 v[242:245], v200, s[58:59] offset:16
.Lp4e_m2_n1:
	v_pk_fma_f32 v[126:127], v[126:127], v[166:167], v[54:55] op_sel_hi:[1,0,1]
	v_pk_fma_f32 v[128:129], v[128:129], v[166:167], v[56:57] op_sel_hi:[1,0,1]
	v_pk_fma_f32 v[122:123], v[122:123], v[166:167], v[50:51] op_sel_hi:[1,0,1]
	v_pk_fma_f32 v[124:125], v[124:125], v[166:167], v[52:53] op_sel_hi:[1,0,1]
	v_pk_fma_f32 v[118:119], v[118:119], v[166:167], v[46:47] op_sel_hi:[1,0,1]
	v_pk_fma_f32 v[120:121], v[120:121], v[166:167], v[48:49] op_sel_hi:[1,0,1]
	v_pk_fma_f32 v[114:115], v[114:115], v[166:167], v[42:43] op_sel_hi:[1,0,1]
	v_pk_fma_f32 v[116:117], v[116:117], v[166:167], v[44:45] op_sel_hi:[1,0,1]
	s_cmp_lg_u32 s8, 8
	s_cbranch_scc1 .Lp4e_m2_w1
	s_waitcnt vmcnt(4)

; __device__ __forceinline__ u32x4 pack8(const f32x4 a, const f32x4 b) { u32x4 w; w.x = cvt_pk_bf16(a[0], a[1]); w.y = cvt_pk_bf16(a[2], a[3]); w.z = cvt_pk_bf16(b[0], b[1]); w.w = cvt_pk_bf16(b[2], b[3]); return w; }
; #define ROPE_LOAD(C0, C1, S0, S1, r_) do { const int pos_ = (u.pm * BM + ((r_) >> 2) * HALF + wr * 64 + ((r_) & 3) * 16 + fr) & (SEQ - 1); const float* cp_ = cosT + pos_ * 32 + fq * 8; const float* sp_ = sinT + pos_ * 32 + fq * 8; \
;             C0 = *(const f32x4*)cp_; C1 = *(const f32x4*)(cp_ + 4); S0 = *(const f32x4*)sp_; S1 = *(const f32x4*)(sp_ + 4); } while (0)
;     __device__ __forceinline__ void operator()(const f32x4 (&acc)[2][2][4][2], const Unit& u, int wr, int wc, int fr, int fq) const {
;     ...
;                 if (mode == 2) { f32x4 cA, cB, sA, sB; ROPE_LOAD(cA, cB, sA, sB, r); const f32x4 x0 = a0, x1 = a1, y0 = b0, y1 = b1;
;                     a0 = x0 * cA - y0 * sA; a1 = x1 * cB - y1 * sB; b0 = y0 * cA + x0 * sA; b1 = y1 * cB + x1 * sB; }
;                 store_lines(stg + (wr * 4 + wc) * 1024, pack8(a0, a1), pack8(b0, b1), fr, fq, dst + (size_t)(row - fr) * pitch + (c0 - fq * 8), pitch); } }
.Lp4e_m2_v1:
	s_waitcnt vmcnt(6)
	v_pk_mul_f32 v[212:213], v[118:119], v[148:149]
	v_pk_mul_f32 v[214:215], v[120:121], v[150:151]
	v_pk_mul_f32 v[216:217], v[114:115], v[152:153]
	v_pk_mul_f32 v[218:219], v[116:117], v[154:155]
	v_pk_fma_f32 v[212:213], v[126:127], v[222:223], v[212:213] neg_lo:[0,0,1] neg_hi:[0,0,1]
	v_pk_fma_f32 v[214:215], v[128:129], v[224:225], v[214:215] neg_lo:[0,0,1] neg_hi:[0,0,1]
	v_pk_fma_f32 v[216:217], v[122:123], v[246:247], v[216:217] neg_lo:[0,0,1] neg_hi:[0,0,1]
	v_pk_fma_f32 v[218:219], v[124:125], v[248:249], v[218:219] neg_lo:[0,0,1] neg_hi:[0,0,1]
	v_pk_mul_f32 v[126:127], v[126:127], v[148:149]
	v_pk_mul_f32 v[128:129], v[128:129], v[150:151]
	v_pk_mul_f32 v[122:123], v[122:123], v[152:153]
	v_pk_mul_f32 v[124:125], v[124:125], v[154:155]
	v_pk_fma_f32 v[118:119], v[118:119], v[222:223], v[126:127]
	v_pk_fma_f32 v[120:121], v[120:121], v[224:225], v[128:129]
	v_pk_fma_f32 v[114:115], v[114:115], v[246:247], v[122:123]
	v_pk_fma_f32 v[116:117], v[116:117], v[248:249], v[124:125]
	v_cvt_pk_bf16_f32 v172, v212, v213
	v_cvt_pk_bf16_f32 v173, v214, v215
	v_cvt_pk_bf16_f32 v174, v216, v217
	v_cvt_pk_bf16_f32 v175, v218, v219
	v_cvt_pk_bf16_f32 v196, v118, v119
	v_cvt_pk_bf16_f32 v197, v120, v121
	v_cvt_pk_bf16_f32 v198, v114, v115
	v_cvt_pk_bf16_f32 v199, v116, v117
	ds_write_b128 v177, v[172:175]
	ds_write_b128 v177, v[196:199] offset:64
	ds_read_b128 v[212:215], v186
	ds_read_b128 v[216:219], v186 offset:8192
	s_waitcnt lgkmcnt(1)
	global_store_dwordx4 v176, v[212:215], s[100:101]
	s_waitcnt lgkmcnt(0)
	global_store_dwordx4 v176, v[216:219], s[98:99]
	s_add_i32 s8, s8, -1
	s_cmp_eq_u32 s8, 0
	s_cbranch_scc1 .Lp4e_end
.Lp4e_m2_rg2:
	s_lshl_b32 s52, 32, s10
	s_add_u32 s100, s28, s52
	s_addc_u32 s101, s29, 0
	s_add_u32 s98, s100, s53
	s_addc_u32 s99, s101, 0
	s_cmp_eq_u32 s8, 1
	s_cbranch_scc1 .Lp4e_m2_n2
	s_movk_i32 s54, 0x30
	s_add_i32 s54, s31, s54
	s_and_b32 s54, s54, 0x1fff
	s_lshl_b32 s54, s54, 7
	s_add_u32 s56, s18, s54
	s_addc_u32 s57, s19, 0
	s_add_u32 s58, s20, s54
	s_addc_u32 s59, s21, 0
	global_load_dwordx4 v[222:225], v200, s[56:57]
	global_load_dwordx4 v[246:249], v200, s[56:57] offset:16
	global_load_dwordx4 v[148:151], v200, s[58:59]
	global_load_dwordx4 v[152:155], v200, s[58:59] offset:16
.Lp4e_m2_n2:
	v_pk_fma_f32 v[110:111], v[110:111], v[168:169], v[54:55] op_sel_hi:[1,0,1]
	v_pk_fma_f32 v[112:113], v[112:113], v[168:169], v[56:57] op_sel_hi:[1,0,1]
	v_pk_fma_f32 v[106:107], v[106:107], v[168:169], v[50:51] op_sel_hi:[1,0,1]
	v_pk_fma_f32 v[108:109], v[108:109], v[168:169], v[52:53] op_sel_hi:[1,0,1]
	v_pk_fma_f32 v[102:103], v[102:103], v[168:169], v[46:47] op_sel_hi:[1,0,1]
	v_pk_fma_f32 v[104:105], v[104:105], v[168:169], v[48:49] op_sel_hi:[1,0,1]
	v_pk_fma_f32 v[98:99], v[98:99], v[168:169], v[42:43] op_sel_hi:[1,0,1]
	v_pk_fma_f32 v[100:101], v[100:101], v[168:169], v[44:45] op_sel_hi:[1,0,1]
	s_cmp_lg_u32 s8, 8
	s_cbranch_scc1 .Lp4e_m2_w2
	s_waitcnt vmcnt(4)

; __device__ __forceinline__ u32x4 pack8(const f32x4 a, const f32x4 b) { u32x4 w; w.x = cvt_pk_bf16(a[0], a[1]); w.y = cvt_pk_bf16(a[2], a[3]); w.z = cvt_pk_bf16(b[0], b[1]); w.w = cvt_pk_bf16(b[2], b[3]); return w; }
; #define ROPE_LOAD(C0, C1, S0, S1, r_) do { const int pos_ = (u.pm * BM + ((r_) >> 2) * HALF + wr * 64 + ((r_) & 3) * 16 + fr) & (SEQ - 1); const float* cp_ = cosT + pos_ * 32 + fq * 8; const float* sp_ = sinT + pos_ * 32 + fq * 8; \
;             C0 = *(const f32x4*)cp_; C1 = *(const f32x4*)(cp_ + 4); S0 = *(const f32x4*)sp_; S1 = *(const f32x4*)(sp_ + 4); } while (0)
;     __device__ __forceinline__ void operator()(const f32x4 (&acc)[2][2][4][2], const Unit& u, int wr, int wc, int fr, int fq) const {
;     ...
;                 if (mode == 2) { f32x4 cA, cB, sA, sB; ROPE_LOAD(cA, cB, sA, sB, r); const f32x4 x0 = a0, x1 = a1, y0 = b0, y1 = b1;
;                     a0 = x0 * cA - y0 * sA; a1 = x1 * cB - y1 * sB; b0 = y0 * cA + x0 * sA; b1 = y1 * cB + x1 * sB; }
;                 store_lines(stg + (wr * 4 + wc) * 1024, pack8(a0, a1), pack8(b0, b1), fr, fq, dst + (size_t)(row - fr) * pitch + (c0 - fq * 8), pitch); } }
.Lp4e_m2_v2:
	s_waitcnt vmcnt(6)
	v_pk_mul_f32 v[212:213], v[102:103], v[238:239]
	v_pk_mul_f32 v[214:215], v[104:105], v[240:241]
	v_pk_mul_f32 v[216:217], v[98:99], v[242:243]
	v_pk_mul_f32 v[218:219], v[100:101], v[244:245]
	v_pk_fma_f32 v[212:213], v[110:111], v[230:231], v[212:213] neg_lo:[0,0,1] neg_hi:[0,0,1]
	v_pk_fma_f32 v[214:215], v[112:113], v[232:233], v[214:215] neg_lo:[0,0,1] neg_hi:[0,0,1]
	v_pk_fma_f32 v[216:217], v[106:107], v[234:235], v[216:217] neg_lo:[0,0,1] neg_hi:[0,0,1]
	v_pk_fma_f32 v[218:219], v[108:109], v[236:237], v[218:219] neg_lo:[0,0,1] neg_hi:[0,0,1]
	v_pk_mul_f32 v[110:111], v[110:111], v[238:239]
	v_pk_mul_f32 v[112:113], v[112:113], v[240:241]
	v_pk_mul_f32 v[106:107], v[106:107], v[242:243]
	v_pk_mul_f32 v[108:109], v[108:109], v[244:245]
	v_pk_fma_f32 v[102:103], v[102:103], v[230:231], v[110:111]
	v_pk_fma_f32 v[104:105], v[104:105], v[232:233], v[112:113]
	v_pk_fma_f32 v[98:99], v[98:99], v[234:235], v[106:107]
	v_pk_fma_f32 v[100:101], v[100:101], v[236:237], v[108:109]
	v_cvt_pk_bf16_f32 v172, v212, v213
	v_cvt_pk_bf16_f32 v173, v214, v215
	v_cvt_pk_bf16_f32 v174, v216, v217
	v_cvt_pk_bf16_f32 v175, v218, v219
	v_cvt_pk_bf16_f32 v196, v102, v103
	v_cvt_pk_bf16_f32 v197, v104, v105
	v_cvt_pk_bf16_f32 v198, v98, v99
	v_cvt_pk_bf16_f32 v199, v100, v101
	ds_write_b128 v177, v[172:175]
	ds_write_b128 v177, v[196:199] offset:64
	ds_read_b128 v[212:215], v186
	ds_read_b128 v[216:219], v186 offset:8192
	s_waitcnt lgkmcnt(1)
	global_store_dwordx4 v176, v[212:215], s[100:101]
	s_waitcnt lgkmcnt(0)
	global_store_dwordx4 v176, v[216:219], s[98:99]
	s_add_i32 s8, s8, -1
	s_cmp_eq_u32 s8, 0
	s_cbranch_scc1 .Lp4e_end
.Lp4e_m2_rg3:
	s_lshl_b32 s52, 48, s10
	s_add_u32 s100, s28, s52
	s_addc_u32 s101, s29, 0
	s_add_u32 s98, s100, s53
	s_addc_u32 s99, s101, 0
	s_cmp_eq_u32 s8, 1
	s_cbranch_scc1 .Lp4e_m2_n3
	s_movk_i32 s54, 0x80
	s_add_i32 s54, s31, s54
	s_and_b32 s54, s54, 0x1fff
	s_lshl_b32 s54, s54, 7
	s_add_u32 s56, s18, s54
	s_addc_u32 s57, s19, 0
	s_add_u32 s58, s20, s54
	s_addc_u32 s59, s21, 0
	global_load_dwordx4 v[230:233], v200, s[56:57]
	global_load_dwordx4 v[234:237], v200, s[56:57] offset:16
	global_load_dwordx4 v[238:241], v200, s[58:59]
	global_load_dwordx4 v[242:245], v200, s[58:59] offset:16
.Lp4e_m2_n3:
	v_pk_fma_f32 v[94:95], v[94:95], v[170:171], v[54:55] op_sel_hi:[1,0,1]
	v_pk_fma_f32 v[96:97], v[96:97], v[170:171], v[56:57] op_sel_hi:[1,0,1]
	v_pk_fma_f32 v[90:91], v[90:91], v[170:171], v[50:51] op_sel_hi:[1,0,1]
	v_pk_fma_f32 v[92:93], v[92:93], v[170:171], v[52:53] op_sel_hi:[1,0,1]
	v_pk_fma_f32 v[86:87], v[86:87], v[170:171], v[46:47] op_sel_hi:[1,0,1]
	v_pk_fma_f32 v[88:89], v[88:89], v[170:171], v[48:49] op_sel_hi:[1,0,1]
	v_pk_fma_f32 v[82:83], v[82:83], v[170:171], v[42:43] op_sel_hi:[1,0,1]
	v_pk_fma_f32 v[84:85], v[84:85], v[170:171], v[44:45] op_sel_hi:[1,0,1]
	s_cmp_lg_u32 s8, 8
	s_cbranch_scc1 .Lp4e_m2_w3
	s_waitcnt vmcnt(4)

; __device__ __forceinline__ u32x4 pack8(const f32x4 a, const f32x4 b) { u32x4 w; w.x = cvt_pk_bf16(a[0], a[1]); w.y = cvt_pk_bf16(a[2], a[3]); w.z = cvt_pk_bf16(b[0], b[1]); w.w = cvt_pk_bf16(b[2], b[3]); return w; }
; #define ROPE_LOAD(C0, C1, S0, S1, r_) do { const int pos_ = (u.pm * BM + ((r_) >> 2) * HALF + wr * 64 + ((r_) & 3) * 16 + fr) & (SEQ - 1); const float* cp_ = cosT + pos_ * 32 + fq * 8; const float* sp_ = sinT + pos_ * 32 + fq * 8; \
;             C0 = *(const f32x4*)cp_; C1 = *(const f32x4*)(cp_ + 4); S0 = *(const f32x4*)sp_; S1 = *(const f32x4*)(sp_ + 4); } while (0)
;     __device__ __forceinline__ void operator()(const f32x4 (&acc)[2][2][4][2], const Unit& u, int wr, int wc, int fr, int fq) const {
;     ...
;                 if (mode == 2) { f32x4 cA, cB, sA, sB; ROPE_LOAD(cA, cB, sA, sB, r); const f32x4 x0 = a0, x1 = a1, y0 = b0, y1 = b1;
;                     a0 = x0 * cA - y0 * sA; a1 = x1 * cB - y1 * sB; b0 = y0 * cA + x0 * sA; b1 = y1 * cB + x1 * sB; }
;                 store_lines(stg + (wr * 4 + wc) * 1024, pack8(a0, a1), pack8(b0, b1), fr, fq, dst + (size_t)(row - fr) * pitch + (c0 - fq * 8), pitch); } }
.Lp4e_m2_v3:
	s_waitcnt vmcnt(6)
	v_pk_mul_f32 v[212:213], v[86:87], v[148:149]
	v_pk_mul_f32 v[214:215], v[88:89], v[150:151]
	v_pk_mul_f32 v[216:217], v[82:83], v[152:153]
	v_pk_mul_f32 v[218:219], v[84:85], v[154:155]
	v_pk_fma_f32 v[212:213], v[94:95], v[222:223], v[212:213] neg_lo:[0,0,1] neg_hi:[0,0,1]
	v_pk_fma_f32 v[214:215], v[96:97], v[224:225], v[214:215] neg_lo:[0,0,1] neg_hi:[0,0,1]
	v_pk_fma_f32 v[216:217], v[90:91], v[246:247], v[216:217] neg_lo:[0,0,1] neg_hi:[0,0,1]
	v_pk_fma_f32 v[218:219], v[92:93], v[248:249], v[218:219] neg_lo:[0,0,1] neg_hi:[0,0,1]
	v_pk_mul_f32 v[94:95], v[94:95], v[148:149]
	v_pk_mul_f32 v[96:97], v[96:97], v[150:151]
	v_pk_mul_f32 v[90:91], v[90:91], v[152:153]
	v_pk_mul_f32 v[92:93], v[92:93], v[154:155]
	v_pk_fma_f32 v[86:87], v[86:87], v[222:223], v[94:95]
	v_pk_fma_f32 v[88:89], v[88:89], v[224:225], v[96:97]
	v_pk_fma_f32 v[82:83], v[82:83], v[246:247], v[90:91]
	v_pk_fma_f32 v[84:85], v[84:85], v[248:249], v[92:93]
	v_cvt_pk_bf16_f32 v172, v212, v213
	v_cvt_pk_bf16_f32 v173, v214, v215
	v_cvt_pk_bf16_f32 v174, v216, v217
	v_cvt_pk_bf16_f32 v175, v218, v219
	v_cvt_pk_bf16_f32 v196, v86, v87
	v_cvt_pk_bf16_f32 v197, v88, v89
	v_cvt_pk_bf16_f32 v198, v82, v83
	v_cvt_pk_bf16_f32 v199, v84, v85
	ds_write_b128 v177, v[172:175]
	ds_write_b128 v177, v[196:199] offset:64
	ds_read_b128 v[212:215], v186
	ds_read_b128 v[216:219], v186 offset:8192
	s_waitcnt lgkmcnt(1)
	global_store_dwordx4 v176, v[212:215], s[100:101]
	s_waitcnt lgkmcnt(0)
	global_store_dwordx4 v176, v[216:219], s[98:99]
	s_add_i32 s8, s8, -1
	s_cmp_eq_u32 s8, 0
	s_cbranch_scc1 .Lp4e_end
.Lp4e_m2_rg4:
	s_lshl_b32 s52, 128, s10
	s_add_u32 s100, s28, s52
	s_addc_u32 s101, s29, 0
	s_add_u32 s98, s100, s53
	s_addc_u32 s99, s101, 0
	s_cmp_eq_u32 s8, 1
	s_cbranch_scc1 .Lp4e_m2_n4
	s_movk_i32 s54, 0x90
	s_add_i32 s54, s31, s54
	s_and_b32 s54, s54, 0x1fff
	s_lshl_b32 s54, s54, 7
	s_add_u32 s56, s18, s54
	s_addc_u32 s57, s19, 0
	s_add_u32 s58, s20, s54
	s_addc_u32 s59, s21, 0
	global_load_dwordx4 v[222:225], v200, s[56:57]
	global_load_dwordx4 v[246:249], v200, s[56:57] offset:16
	global_load_dwordx4 v[148:151], v200, s[58:59]
	global_load_dwordx4 v[152:155], v200, s[58:59] offset:16
.Lp4e_m2_n4:
	v_pk_fma_f32 v[78:79], v[78:79], v[156:157], v[54:55] op_sel_hi:[1,0,1]
	v_pk_fma_f32 v[80:81], v[80:81], v[156:157], v[56:57] op_sel_hi:[1,0,1]
	v_pk_fma_f32 v[74:75], v[74:75], v[156:157], v[50:51] op_sel_hi:[1,0,1]
	v_pk_fma_f32 v[76:77], v[76:77], v[156:157], v[52:53] op_sel_hi:[1,0,1]
	v_pk_fma_f32 v[70:71], v[70:71], v[156:157], v[46:47] op_sel_hi:[1,0,1]
	v_pk_fma_f32 v[72:73], v[72:73], v[156:157], v[48:49] op_sel_hi:[1,0,1]
	v_pk_fma_f32 v[66:67], v[66:67], v[156:157], v[42:43] op_sel_hi:[1,0,1]
	v_pk_fma_f32 v[68:69], v[68:69], v[156:157], v[44:45] op_sel_hi:[1,0,1]
	s_cmp_lg_u32 s8, 8
	s_cbranch_scc1 .Lp4e_m2_w4
	s_waitcnt vmcnt(4)

; __device__ __forceinline__ u32x4 pack8(const f32x4 a, const f32x4 b) { u32x4 w; w.x = cvt_pk_bf16(a[0], a[1]); w.y = cvt_pk_bf16(a[2], a[3]); w.z = cvt_pk_bf16(b[0], b[1]); w.w = cvt_pk_bf16(b[2], b[3]); return w; }
; #define ROPE_LOAD(C0, C1, S0, S1, r_) do { const int pos_ = (u.pm * BM + ((r_) >> 2) * HALF + wr * 64 + ((r_) & 3) * 16 + fr) & (SEQ - 1); const float* cp_ = cosT + pos_ * 32 + fq * 8; const float* sp_ = sinT + pos_ * 32 + fq * 8; \
;             C0 = *(const f32x4*)cp_; C1 = *(const f32x4*)(cp_ + 4); S0 = *(const f32x4*)sp_; S1 = *(const f32x4*)(sp_ + 4); } while (0)
;     __device__ __forceinline__ void operator()(const f32x4 (&acc)[2][2][4][2], const Unit& u, int wr, int wc, int fr, int fq) const {
;     ...
;                 if (mode == 2) { f32x4 cA, cB, sA, sB; ROPE_LOAD(cA, cB, sA, sB, r); const f32x4 x0 = a0, x1 = a1, y0 = b0, y1 = b1;
;                     a0 = x0 * cA - y0 * sA; a1 = x1 * cB - y1 * sB; b0 = y0 * cA + x0 * sA; b1 = y1 * cB + x1 * sB; }
;                 store_lines(stg + (wr * 4 + wc) * 1024, pack8(a0, a1), pack8(b0, b1), fr, fq, dst + (size_t)(row - fr) * pitch + (c0 - fq * 8), pitch); } }
.Lp4e_m2_v4:
	s_waitcnt vmcnt(6)
	v_pk_mul_f32 v[212:213], v[70:71], v[238:239]
	v_pk_mul_f32 v[214:215], v[72:73], v[240:241]
	v_pk_mul_f32 v[216:217], v[66:67], v[242:243]
	v_pk_mul_f32 v[218:219], v[68:69], v[244:245]
	v_pk_fma_f32 v[212:213], v[78:79], v[230:231], v[212:213] neg_lo:[0,0,1] neg_hi:[0,0,1]
	v_pk_fma_f32 v[214:215], v[80:81], v[232:233], v[214:215] neg_lo:[0,0,1] neg_hi:[0,0,1]
	v_pk_fma_f32 v[216:217], v[74:75], v[234:235], v[216:217] neg_lo:[0,0,1] neg_hi:[0,0,1]
	v_pk_fma_f32 v[218:219], v[76:77], v[236:237], v[218:219] neg_lo:[0,0,1] neg_hi:[0,0,1]
	v_pk_mul_f32 v[78:79], v[78:79], v[238:239]
	v_pk_mul_f32 v[80:81], v[80:81], v[240:241]
	v_pk_mul_f32 v[74:75], v[74:75], v[242:243]
	v_pk_mul_f32 v[76:77], v[76:77], v[244:245]
	v_pk_fma_f32 v[70:71], v[70:71], v[230:231], v[78:79]
	v_pk_fma_f32 v[72:73], v[72:73], v[232:233], v[80:81]
	v_pk_fma_f32 v[66:67], v[66:67], v[234:235], v[74:75]
	v_pk_fma_f32 v[68:69], v[68:69], v[236:237], v[76:77]
	v_cvt_pk_bf16_f32 v172, v212, v213
	v_cvt_pk_bf16_f32 v173, v214, v215
	v_cvt_pk_bf16_f32 v174, v216, v217
	v_cvt_pk_bf16_f32 v175, v218, v219
	v_cvt_pk_bf16_f32 v196, v70, v71
	v_cvt_pk_bf16_f32 v197, v72, v73
	v_cvt_pk_bf16_f32 v198, v66, v67
	v_cvt_pk_bf16_f32 v199, v68, v69
	ds_write_b128 v177, v[172:175]
	ds_write_b128 v177, v[196:199] offset:64
	ds_read_b128 v[212:215], v186
	ds_read_b128 v[216:219], v186 offset:8192
	s_waitcnt lgkmcnt(1)
	global_store_dwordx4 v176, v[212:215], s[100:101]
	s_waitcnt lgkmcnt(0)
	global_store_dwordx4 v176, v[216:219], s[98:99]
	s_add_i32 s8, s8, -1
	s_cmp_eq_u32 s8, 0
	s_cbranch_scc1 .Lp4e_end
.Lp4e_m2_rg5:
	s_lshl_b32 s52, 144, s10
	s_add_u32 s100, s28, s52
	s_addc_u32 s101, s29, 0
	s_add_u32 s98, s100, s53
	s_addc_u32 s99, s101, 0
	s_cmp_eq_u32 s8, 1
	s_cbranch_scc1 .Lp4e_m2_n5
	s_movk_i32 s54, 0xa0
	s_add_i32 s54, s31, s54
	s_and_b32 s54, s54, 0x1fff
	s_lshl_b32 s54, s54, 7
	s_add_u32 s56, s18, s54
	s_addc_u32 s57, s19, 0
	s_add_u32 s58, s20, s54
	s_addc_u32 s59, s21, 0
	global_load_dwordx4 v[230:233], v200, s[56:57]
	global_load_dwordx4 v[234:237], v200, s[56:57] offset:16
	global_load_dwordx4 v[238:241], v200, s[58:59]
	global_load_dwordx4 v[242:245], v200, s[58:59] offset:16
.Lp4e_m2_n5:
	v_pk_fma_f32 v[62:63], v[62:63], v[158:159], v[54:55] op_sel_hi:[1,0,1]
	v_pk_fma_f32 v[64:65], v[64:65], v[158:159], v[56:57] op_sel_hi:[1,0,1]
	v_pk_fma_f32 v[58:59], v[58:59], v[158:159], v[50:51] op_sel_hi:[1,0,1]
	v_pk_fma_f32 v[60:61], v[60:61], v[158:159], v[52:53] op_sel_hi:[1,0,1]
	v_pk_fma_f32 v[38:39], v[38:39], v[158:159], v[46:47] op_sel_hi:[1,0,1]
	v_pk_fma_f32 v[40:41], v[40:41], v[158:159], v[48:49] op_sel_hi:[1,0,1]
	v_pk_fma_f32 v[34:35], v[34:35], v[158:159], v[42:43] op_sel_hi:[1,0,1]
	v_pk_fma_f32 v[36:37], v[36:37], v[158:159], v[44:45] op_sel_hi:[1,0,1]
	s_cmp_lg_u32 s8, 8
	s_cbranch_scc1 .Lp4e_m2_w5
	s_waitcnt vmcnt(4)

; __device__ __forceinline__ u32x4 pack8(const f32x4 a, const f32x4 b) { u32x4 w; w.x = cvt_pk_bf16(a[0], a[1]); w.y = cvt_pk_bf16(a[2], a[3]); w.z = cvt_pk_bf16(b[0], b[1]); w.w = cvt_pk_bf16(b[2], b[3]); return w; }
; #define ROPE_LOAD(C0, C1, S0, S1, r_) do { const int pos_ = (u.pm * BM + ((r_) >> 2) * HALF + wr * 64 + ((r_) & 3) * 16 + fr) & (SEQ - 1); const float* cp_ = cosT + pos_ * 32 + fq * 8; const float* sp_ = sinT + pos_ * 32 + fq * 8; \
;             C0 = *(const f32x4*)cp_; C1 = *(const f32x4*)(cp_ + 4); S0 = *(const f32x4*)sp_; S1 = *(const f32x4*)(sp_ + 4); } while (0)
;     __device__ __forceinline__ void operator()(const f32x4 (&acc)[2][2][4][2], const Unit& u, int wr, int wc, int fr, int fq) const {
;     ...
;                 if (mode == 2) { f32x4 cA, cB, sA, sB; ROPE_LOAD(cA, cB, sA, sB, r); const f32x4 x0 = a0, x1 = a1, y0 = b0, y1 = b1;
;                     a0 = x0 * cA - y0 * sA; a1 = x1 * cB - y1 * sB; b0 = y0 * cA + x0 * sA; b1 = y1 * cB + x1 * sB; }
;                 store_lines(stg + (wr * 4 + wc) * 1024, pack8(a0, a1), pack8(b0, b1), fr, fq, dst + (size_t)(row - fr) * pitch + (c0 - fq * 8), pitch); } }
.Lp4e_m2_v5:
	s_waitcnt vmcnt(6)
	v_pk_mul_f32 v[212:213], v[38:39], v[148:149]
	v_pk_mul_f32 v[214:215], v[40:41], v[150:151]
	v_pk_mul_f32 v[216:217], v[34:35], v[152:153]
	v_pk_mul_f32 v[218:219], v[36:37], v[154:155]
	v_pk_fma_f32 v[212:213], v[62:63], v[222:223], v[212:213] neg_lo:[0,0,1] neg_hi:[0,0,1]
	v_pk_fma_f32 v[214:215], v[64:65], v[224:225], v[214:215] neg_lo:[0,0,1] neg_hi:[0,0,1]
	v_pk_fma_f32 v[216:217], v[58:59], v[246:247], v[216:217] neg_lo:[0,0,1] neg_hi:[0,0,1]
	v_pk_fma_f32 v[218:219], v[60:61], v[248:249], v[218:219] neg_lo:[0,0,1] neg_hi:[0,0,1]
	v_pk_mul_f32 v[62:63], v[62:63], v[148:149]
	v_pk_mul_f32 v[64:65], v[64:65], v[150:151]
	v_pk_mul_f32 v[58:59], v[58:59], v[152:153]
	v_pk_mul_f32 v[60:61], v[60:61], v[154:155]
	v_pk_fma_f32 v[38:39], v[38:39], v[222:223], v[62:63]
	v_pk_fma_f32 v[40:41], v[40:41], v[224:225], v[64:65]
	v_pk_fma_f32 v[34:35], v[34:35], v[246:247], v[58:59]
	v_pk_fma_f32 v[36:37], v[36:37], v[248:249], v[60:61]
	v_cvt_pk_bf16_f32 v172, v212, v213
	v_cvt_pk_bf16_f32 v173, v214, v215
	v_cvt_pk_bf16_f32 v174, v216, v217
	v_cvt_pk_bf16_f32 v175, v218, v219
	v_cvt_pk_bf16_f32 v196, v38, v39
	v_cvt_pk_bf16_f32 v197, v40, v41
	v_cvt_pk_bf16_f32 v198, v34, v35
	v_cvt_pk_bf16_f32 v199, v36, v37
	ds_write_b128 v177, v[172:175]
	ds_write_b128 v177, v[196:199] offset:64
	ds_read_b128 v[212:215], v186
	ds_read_b128 v[216:219], v186 offset:8192
	s_waitcnt lgkmcnt(1)
	global_store_dwordx4 v176, v[212:215], s[100:101]
	s_waitcnt lgkmcnt(0)
	global_store_dwordx4 v176, v[216:219], s[98:99]
	s_add_i32 s8, s8, -1
	s_cmp_eq_u32 s8, 0
	s_cbranch_scc1 .Lp4e_end
.Lp4e_m2_rg6:
	s_lshl_b32 s52, 160, s10
	s_add_u32 s100, s28, s52
	s_addc_u32 s101, s29, 0
	s_add_u32 s98, s100, s53
	s_addc_u32 s99, s101, 0
	s_cmp_eq_u32 s8, 1
	s_cbranch_scc1 .Lp4e_m2_n6
	s_movk_i32 s54, 0xb0
	s_add_i32 s54, s31, s54
	s_and_b32 s54, s54, 0x1fff
	s_lshl_b32 s54, s54, 7
	s_add_u32 s56, s18, s54
	s_addc_u32 s57, s19, 0
	s_add_u32 s58, s20, s54
	s_addc_u32 s59, s21, 0
	global_load_dwordx4 v[222:225], v200, s[56:57]
	global_load_dwordx4 v[246:249], v200, s[56:57] offset:16
	global_load_dwordx4 v[148:151], v200, s[58:59]
	global_load_dwordx4 v[152:155], v200, s[58:59] offset:16
.Lp4e_m2_n6:
	v_pk_fma_f32 v[30:31], v[30:31], v[160:161], v[54:55] op_sel_hi:[1,0,1]
	v_pk_fma_f32 v[32:33], v[32:33], v[160:161], v[56:57] op_sel_hi:[1,0,1]
	v_pk_fma_f32 v[26:27], v[26:27], v[160:161], v[50:51] op_sel_hi:[1,0,1]
	v_pk_fma_f32 v[28:29], v[28:29], v[160:161], v[52:53] op_sel_hi:[1,0,1]
	v_pk_fma_f32 v[22:23], v[22:23], v[160:161], v[46:47] op_sel_hi:[1,0,1]
	v_pk_fma_f32 v[24:25], v[24:25], v[160:161], v[48:49] op_sel_hi:[1,0,1]
	v_pk_fma_f32 v[18:19], v[18:19], v[160:161], v[42:43] op_sel_hi:[1,0,1]
	v_pk_fma_f32 v[20:21], v[20:21], v[160:161], v[44:45] op_sel_hi:[1,0,1]
	s_cmp_lg_u32 s8, 8
	s_cbranch_scc1 .Lp4e_m2_w6
	s_waitcnt vmcnt(4)

; __device__ __forceinline__ u32x4 pack8(const f32x4 a, const f32x4 b) { u32x4 w; w.x = cvt_pk_bf16(a[0], a[1]); w.y = cvt_pk_bf16(a[2], a[3]); w.z = cvt_pk_bf16(b[0], b[1]); w.w = cvt_pk_bf16(b[2], b[3]); return w; }
; #define ROPE_LOAD(C0, C1, S0, S1, r_) do { const int pos_ = (u.pm * BM + ((r_) >> 2) * HALF + wr * 64 + ((r_) & 3) * 16 + fr) & (SEQ - 1); const float* cp_ = cosT + pos_ * 32 + fq * 8; const float* sp_ = sinT + pos_ * 32 + fq * 8; \
;             C0 = *(const f32x4*)cp_; C1 = *(const f32x4*)(cp_ + 4); S0 = *(const f32x4*)sp_; S1 = *(const f32x4*)(sp_ + 4); } while (0)
;     __device__ __forceinline__ void operator()(const f32x4 (&acc)[2][2][4][2], const Unit& u, int wr, int wc, int fr, int fq) const {
;     ...
;                 if (mode == 2) { f32x4 cA, cB, sA, sB; ROPE_LOAD(cA, cB, sA, sB, r); const f32x4 x0 = a0, x1 = a1, y0 = b0, y1 = b1;
;                     a0 = x0 * cA - y0 * sA; a1 = x1 * cB - y1 * sB; b0 = y0 * cA + x0 * sA; b1 = y1 * cB + x1 * sB; }
;                 store_lines(stg + (wr * 4 + wc) * 1024, pack8(a0, a1), pack8(b0, b1), fr, fq, dst + (size_t)(row - fr) * pitch + (c0 - fq * 8), pitch); } }
.Lp4e_m2_v6:
	s_waitcnt vmcnt(6)
	v_pk_mul_f32 v[212:213], v[22:23], v[238:239]
	v_pk_mul_f32 v[214:215], v[24:25], v[240:241]
	v_pk_mul_f32 v[216:217], v[18:19], v[242:243]
	v_pk_mul_f32 v[218:219], v[20:21], v[244:245]
	v_pk_fma_f32 v[212:213], v[30:31], v[230:231], v[212:213] neg_lo:[0,0,1] neg_hi:[0,0,1]
	v_pk_fma_f32 v[214:215], v[32:33], v[232:233], v[214:215] neg_lo:[0,0,1] neg_hi:[0,0,1]
	v_pk_fma_f32 v[216:217], v[26:27], v[234:235], v[216:217] neg_lo:[0,0,1] neg_hi:[0,0,1]
	v_pk_fma_f32 v[218:219], v[28:29], v[236:237], v[218:219] neg_lo:[0,0,1] neg_hi:[0,0,1]
	v_pk_mul_f32 v[30:31], v[30:31], v[238:239]
	v_pk_mul_f32 v[32:33], v[32:33], v[240:241]
	v_pk_mul_f32 v[26:27], v[26:27], v[242:243]
	v_pk_mul_f32 v[28:29], v[28:29], v[244:245]
	v_pk_fma_f32 v[22:23], v[22:23], v[230:231], v[30:31]
	v_pk_fma_f32 v[24:25], v[24:25], v[232:233], v[32:33]
	v_pk_fma_f32 v[18:19], v[18:19], v[234:235], v[26:27]
	v_pk_fma_f32 v[20:21], v[20:21], v[236:237], v[28:29]
	v_cvt_pk_bf16_f32 v172, v212, v213
	v_cvt_pk_bf16_f32 v173, v214, v215
	v_cvt_pk_bf16_f32 v174, v216, v217
	v_cvt_pk_bf16_f32 v175, v218, v219
	v_cvt_pk_bf16_f32 v196, v22, v23
	v_cvt_pk_bf16_f32 v197, v24, v25
	v_cvt_pk_bf16_f32 v198, v18, v19
	v_cvt_pk_bf16_f32 v199, v20, v21
	ds_write_b128 v177, v[172:175]
	ds_write_b128 v177, v[196:199] offset:64
	ds_read_b128 v[212:215], v186
	ds_read_b128 v[216:219], v186 offset:8192
	s_waitcnt lgkmcnt(1)
	global_store_dwordx4 v176, v[212:215], s[100:101]
	s_waitcnt lgkmcnt(0)
	global_store_dwordx4 v176, v[216:219], s[98:99]
	s_add_i32 s8, s8, -1
	s_cmp_eq_u32 s8, 0
	s_cbranch_scc1 .Lp4e_end
.Lp4e_m2_rg7:
	s_lshl_b32 s52, 176, s10
	s_add_u32 s100, s28, s52
	s_addc_u32 s101, s29, 0
	s_add_u32 s98, s100, s53
	s_addc_u32 s99, s101, 0
	s_cmp_eq_u32 s8, 1
	s_cbranch_scc1 .Lp4e_m2_n7
	s_movk_i32 s54, 0x0
	s_add_i32 s54, s31, s54
	s_and_b32 s54, s54, 0x1fff
	s_lshl_b32 s54, s54, 7
	s_add_u32 s56, s18, s54
	s_addc_u32 s57, s19, 0
	s_add_u32 s58, s20, s54
	s_addc_u32 s59, s21, 0
	global_load_dwordx4 v[230:233], v200, s[56:57]
	global_load_dwordx4 v[234:237], v200, s[56:57] offset:16
	global_load_dwordx4 v[238:241], v200, s[58:59]
	global_load_dwordx4 v[242:245], v200, s[58:59] offset:16
.Lp4e_m2_n7:
	v_pk_fma_f32 v[14:15], v[14:15], v[162:163], v[54:55] op_sel_hi:[1,0,1]
	v_pk_fma_f32 v[16:17], v[16:17], v[162:163], v[56:57] op_sel_hi:[1,0,1]
	v_pk_fma_f32 v[10:11], v[10:11], v[162:163], v[50:51] op_sel_hi:[1,0,1]
	v_pk_fma_f32 v[12:13], v[12:13], v[162:163], v[52:53] op_sel_hi:[1,0,1]
	v_pk_fma_f32 v[6:7], v[6:7], v[162:163], v[46:47] op_sel_hi:[1,0,1]
	v_pk_fma_f32 v[8:9], v[8:9], v[162:163], v[48:49] op_sel_hi:[1,0,1]
	v_pk_fma_f32 v[2:3], v[2:3], v[162:163], v[42:43] op_sel_hi:[1,0,1]
	v_pk_fma_f32 v[4:5], v[4:5], v[162:163], v[44:45] op_sel_hi:[1,0,1]
	s_cmp_lg_u32 s8, 8
	s_cbranch_scc1 .Lp4e_m2_w7
	s_waitcnt vmcnt(4)

; __device__ __forceinline__ u32x4 pack8(const f32x4 a, const f32x4 b) { u32x4 w; w.x = cvt_pk_bf16(a[0], a[1]); w.y = cvt_pk_bf16(a[2], a[3]); w.z = cvt_pk_bf16(b[0], b[1]); w.w = cvt_pk_bf16(b[2], b[3]); return w; }
; #define ROPE_LOAD(C0, C1, S0, S1, r_) do { const int pos_ = (u.pm * BM + ((r_) >> 2) * HALF + wr * 64 + ((r_) & 3) * 16 + fr) & (SEQ - 1); const float* cp_ = cosT + pos_ * 32 + fq * 8; const float* sp_ = sinT + pos_ * 32 + fq * 8; \
;             C0 = *(const f32x4*)cp_; C1 = *(const f32x4*)(cp_ + 4); S0 = *(const f32x4*)sp_; S1 = *(const f32x4*)(sp_ + 4); } while (0)
;     __device__ __forceinline__ void operator()(const f32x4 (&acc)[2][2][4][2], const Unit& u, int wr, int wc, int fr, int fq) const {
;     ...
;                 if (mode == 2) { f32x4 cA, cB, sA, sB; ROPE_LOAD(cA, cB, sA, sB, r); const f32x4 x0 = a0, x1 = a1, y0 = b0, y1 = b1;
;                     a0 = x0 * cA - y0 * sA; a1 = x1 * cB - y1 * sB; b0 = y0 * cA + x0 * sA; b1 = y1 * cB + x1 * sB; }
;                 store_lines(stg + (wr * 4 + wc) * 1024, pack8(a0, a1), pack8(b0, b1), fr, fq, dst + (size_t)(row - fr) * pitch + (c0 - fq * 8), pitch); } }
.Lp4e_m2_v7:
	s_waitcnt vmcnt(6)
	v_pk_mul_f32 v[212:213], v[6:7], v[148:149]
	v_pk_mul_f32 v[214:215], v[8:9], v[150:151]
	v_pk_mul_f32 v[216:217], v[2:3], v[152:153]
	v_pk_mul_f32 v[218:219], v[4:5], v[154:155]
	v_pk_fma_f32 v[212:213], v[14:15], v[222:223], v[212:213] neg_lo:[0,0,1] neg_hi:[0,0,1]
	v_pk_fma_f32 v[214:215], v[16:17], v[224:225], v[214:215] neg_lo:[0,0,1] neg_hi:[0,0,1]
	v_pk_fma_f32 v[216:217], v[10:11], v[246:247], v[216:217] neg_lo:[0,0,1] neg_hi:[0,0,1]
	v_pk_fma_f32 v[218:219], v[12:13], v[248:249], v[218:219] neg_lo:[0,0,1] neg_hi:[0,0,1]
	v_pk_mul_f32 v[14:15], v[14:15], v[148:149]
	v_pk_mul_f32 v[16:17], v[16:17], v[150:151]
	v_pk_mul_f32 v[10:11], v[10:11], v[152:153]
	v_pk_mul_f32 v[12:13], v[12:13], v[154:155]
	v_pk_fma_f32 v[6:7], v[6:7], v[222:223], v[14:15]
	v_pk_fma_f32 v[8:9], v[8:9], v[224:225], v[16:17]
	v_pk_fma_f32 v[2:3], v[2:3], v[246:247], v[10:11]
	v_pk_fma_f32 v[4:5], v[4:5], v[248:249], v[12:13]
	v_cvt_pk_bf16_f32 v172, v212, v213
	v_cvt_pk_bf16_f32 v173, v214, v215
	v_cvt_pk_bf16_f32 v174, v216, v217
	v_cvt_pk_bf16_f32 v175, v218, v219
	v_cvt_pk_bf16_f32 v196, v6, v7
	v_cvt_pk_bf16_f32 v197, v8, v9
	v_cvt_pk_bf16_f32 v198, v2, v3
	v_cvt_pk_bf16_f32 v199, v4, v5
	ds_write_b128 v177, v[172:175]
	ds_write_b128 v177, v[196:199] offset:64
	ds_read_b128 v[212:215], v186
	ds_read_b128 v[216:219], v186 offset:8192
	s_waitcnt lgkmcnt(1)
	global_store_dwordx4 v176, v[212:215], s[100:101]
	s_waitcnt lgkmcnt(0)
	global_store_dwordx4 v176, v[216:219], s[98:99]
	s_add_i32 s8, s8, -1
	s_cmp_eq_u32 s8, 0
	s_cbranch_scc1 .Lp4e_end
	s_branch .Lp4e_m2_rg0
